# v32 with the phase-0 x to bf16 copy issuing a row's eight loads together (was one load per vmcnt(0) wait: eight serialised round trips per row)
# speedup vs baseline: 1.0045x; 1.0045x over previous
.LBB0_159:
	v_add_co_u32_e32 v28, vcc, 0xfffff000, v4
	v_lshl_add_u64 v[24:25], s[4:5], 0, v[2:3]
	s_nop 0
	v_addc_co_u32_e32 v29, vcc, -1, v5, vcc
	s_mov_b32 s0, 0x1bb00000
	v_add_co_u32_e32 v52, vcc, s0, v24
	global_load_dwordx4 v[20:23], v[28:29], off offset:-3072
	s_nop 0
	v_addc_co_u32_e32 v53, vcc, 0, v25, vcc
	global_load_dwordx4 v[24:27], v[28:29], off offset:-2048
	global_load_dwordx4 v[28:31], v[28:29], off offset:-1024
	global_load_dwordx4 v[32:35], v[4:5], off offset:-4096
	global_load_dwordx4 v[36:39], v[4:5], off offset:-3072
	global_load_dwordx4 v[40:43], v[4:5], off offset:-2048
	global_load_dwordx4 v[44:47], v[4:5], off offset:-1024
	global_load_dwordx4 v[48:51], v[4:5], off
	s_waitcnt vmcnt(7)
	v_cvt_pk_bf16_f32 v54, v20, v21
	v_cvt_pk_bf16_f32 v55, v22, v23
	global_store_dwordx2 v[52:53], v[54:55], off
	s_waitcnt vmcnt(7)
	v_cvt_pk_bf16_f32 v56, v24, v25
	v_cvt_pk_bf16_f32 v57, v26, v27
	global_store_dwordx2 v[52:53], v[56:57], off offset:512
	s_waitcnt vmcnt(7)
	v_cvt_pk_bf16_f32 v58, v28, v29
	v_cvt_pk_bf16_f32 v59, v30, v31
	global_store_dwordx2 v[52:53], v[58:59], off offset:1024
	s_waitcnt vmcnt(7)
	v_cvt_pk_bf16_f32 v60, v32, v33
	v_cvt_pk_bf16_f32 v61, v34, v35
	global_store_dwordx2 v[52:53], v[60:61], off offset:1536
	s_waitcnt vmcnt(7)
	v_cvt_pk_bf16_f32 v62, v36, v37
	v_cvt_pk_bf16_f32 v63, v38, v39
	global_store_dwordx2 v[52:53], v[62:63], off offset:2048
	s_waitcnt vmcnt(7)
	v_cvt_pk_bf16_f32 v64, v40, v41
	v_cvt_pk_bf16_f32 v65, v42, v43
	global_store_dwordx2 v[52:53], v[64:65], off offset:2560
	s_waitcnt vmcnt(7)
	v_cvt_pk_bf16_f32 v66, v44, v45
	v_cvt_pk_bf16_f32 v67, v46, v47
	global_store_dwordx2 v[52:53], v[66:67], off offset:3072
	v_mul_f32_e32 v11, v21, v21
	s_waitcnt lgkmcnt(0)
	v_mul_f32_e32 v15, v23, v23
	v_fmac_f32_e32 v11, v20, v20
	v_fmac_f32_e32 v15, v22, v22
	v_add_f32_e32 v11, v11, v15
	s_waitcnt vmcnt(7)
	v_cvt_pk_bf16_f32 v20, v48, v49
	v_mul_f32_e32 v15, v25, v25
	v_mul_f32_e32 v19, v27, v27
	v_fmac_f32_e32 v15, v24, v24
	v_fmac_f32_e32 v19, v26, v26
	v_add_f32_e32 v15, v15, v19
	v_add_f32_e32 v11, v11, v15
	v_mul_f32_e32 v15, v29, v29
	v_mul_f32_e32 v19, v31, v31
	v_fmac_f32_e32 v15, v28, v28
	v_fmac_f32_e32 v19, v30, v30
	v_add_f32_e32 v15, v15, v19
	v_add_f32_e32 v11, v11, v15
	v_mul_f32_e32 v15, v33, v33
	v_mul_f32_e32 v19, v35, v35
	v_fmac_f32_e32 v15, v32, v32
	v_fmac_f32_e32 v19, v34, v34
	v_add_f32_e32 v15, v15, v19
	v_add_f32_e32 v11, v11, v15
	v_mul_f32_e32 v15, v37, v37
	v_mul_f32_e32 v19, v39, v39
	v_fmac_f32_e32 v15, v36, v36
	v_fmac_f32_e32 v19, v38, v38
	v_add_f32_e32 v15, v15, v19
	v_add_f32_e32 v11, v11, v15
	v_mul_f32_e32 v15, v41, v41
	v_mul_f32_e32 v19, v43, v43
	v_fmac_f32_e32 v15, v40, v40
	v_fmac_f32_e32 v19, v42, v42
	v_add_f32_e32 v15, v15, v19
	v_add_f32_e32 v11, v11, v15
	v_mul_f32_e32 v15, v45, v45
	v_mul_f32_e32 v19, v47, v47
	v_fmac_f32_e32 v15, v44, v44
	v_fmac_f32_e32 v19, v46, v46
	v_add_f32_e32 v15, v15, v19
	v_add_f32_e32 v11, v11, v15
	v_mul_f32_e32 v15, v49, v49
	v_mul_f32_e32 v19, v51, v51
	v_fmac_f32_e32 v15, v48, v48
	v_fmac_f32_e32 v19, v50, v50
	v_add_f32_e32 v15, v15, v19
	v_add_f32_e32 v11, v11, v15
	ds_bpermute_b32 v15, v6, v11
	v_cvt_pk_bf16_f32 v21, v50, v51
	global_store_dwordx2 v[52:53], v[20:21], off offset:3584
	s_waitcnt lgkmcnt(0)
	v_add_f32_e32 v11, v11, v15
	ds_bpermute_b32 v15, v7, v11
	s_waitcnt lgkmcnt(0)
	v_add_f32_e32 v11, v11, v15
	ds_bpermute_b32 v15, v14, v11
	s_waitcnt lgkmcnt(0)
	v_add_f32_e32 v11, v11, v15
	ds_bpermute_b32 v15, v16, v11
	s_waitcnt lgkmcnt(0)
	v_add_f32_e32 v11, v11, v15
	ds_bpermute_b32 v15, v17, v11
	s_waitcnt lgkmcnt(0)
	v_add_f32_e32 v11, v11, v15
	ds_bpermute_b32 v15, v18, v11
	s_and_saveexec_b64 s[20:21], s[38:39]
	s_cbranch_execz .LBB0_158
	s_waitcnt lgkmcnt(0)
	v_add_f32_e32 v11, v11, v15
	v_mul_f32_e32 v11, 0x49800000, v11
	v_trunc_f32_e32 v11, v11
	v_mul_f32_e32 v15, 0x2f800000, v11
	v_floor_f32_e32 v15, v15
	v_fmac_f32_e32 v11, 0xcf800000, v15
	v_cvt_u32_f32_e32 v20, v11
	v_cvt_u32_f32_e32 v21, v15
	v_lshl_add_u64 v[22:23], s[4:5], 0, v[0:1]
	global_store_dwordx2 v[22:23], v[20:21], off
	s_branch .LBB0_158
